# per-half A/B of lever 4 in the attention main loop: static s_setprio 1 on the older half (waves 0-3) instead of waves 4-7; on v104
# baseline (speedup 1.0000x reference)
; #define WAIT_BAR(N) asm volatile("s_waitcnt vmcnt(" #N ") lgkmcnt(0)\n\ts_barrier":::"memory")
;   #define DMA_K(t,slot) glds16(ksrc+(long)(t)*KVBLK*PQ,(unsigned)__builtin_amdgcn_readfirstlane(kdst+(slot)))
;   #define DMA_V(t,slot) glds16(vsrc+(long)(t)*KVBLK*PQ,(unsigned)__builtin_amdgcn_readfirstlane(vdst+(slot)))
;   #define CMASK(P0,P1,t) do{int jb_=(t)-(NT-4); if(jb_>=0)cmask(P0,P1,jb_,qrel,hi);}while(0)
;   #define START(P0,P1) do{ const float rm=rowmax(P0,P1); resc=false; \
;     { const float dl=rm; mhat=fadd_s(mhat,dl); \
;       _Pragma("unroll") for(int r=0;r<16;++r){P0[r]=fsub_s(P0[r],dl);P1[r]=fsub_s(P1[r],dl);} \
;       _Pragma("unroll") for(int r=0;r<16;++r)negm[r]=-mhat; asm volatile("":"+v"(negm)); } \
;     _Pragma("unroll") for(int r=0;r<16;++r)P0[r]=__builtin_amdgcn_exp2f(P0[r]); }while(0)
;   #define CMASK(P0,P1,t) do{}while(0)
;   #define CMASK(P0,P1,t) do{}while(0)
; template<int THRL> __device__ __forceinline__ void attn_unit128(int qb,const bf16*Qh,const bf16*__restrict__ Kh,const bf16*__restrict__ Vh,bf16*Oh,char*shm){
;     ...
;   const int vb0=(int)(lds0+L_V)+((lane>>4)&1)*32+(lane&3)*8+(4*hi+((lane&15)>>2))*64;
;   const char*Kbase=shm+L_K; bf16x8 kf[8];
;   const lds_cptr shm3=(lds_cptr)shm; const lds_cptr kp0=shm3+L_K+hi*1024+r32*16; const lds_cptr vp0=shm3+L_V+((lane>>4)&1)*32+(lane&3)*8+(4*hi+((lane&15)>>2))*64;
;   const lds_cptr qp=shm3+L_Q+wid*4096+lane*16;
;     ...
;   const int NT=(q0+QB)/KVBLK;
;   DMA_K(0,0);DMA_V(0,0);DMA_K(1,KSLOT);
;   #pragma unroll
;   for(int d0=0;d0<4;++d0)glds16(&Qw[(long)r32*PQ+d0*16+hi*8],(unsigned)__builtin_amdgcn_readfirstlane(qdst+d0*1024));
;   float mhat=0.f,l_reg=0.f;f32x16 o[4];o[0]=f32x16{};o[1]=f32x16{};o[2]=f32x16{};o[3]=f32x16{};
;   const f32x16 zero16=f32x16{};
;   const int qrel=wid*QBLK+r32;
;     ...
;   bool resc=false;
;     ...
;   f32x16 pA0,pA1,pB0,pB1;
;   int sl_prev=0,sl_cur=0,sl_next=KSLOT;
;     ...
;   DMA_K(2,2*KSLOT);
;   WAIT_BAR(1);
;   { bf16x8 q4[4];
;     #pragma unroll
;     for(int d0=0;d0<4;++d0)q4[d0]=QLD(d0);
;     qkt(pA0,pA1,Kbase,q4,zero16,r32,hi); }
;   asm volatile("s_nop 15\n\ts_nop 7":"+v"(pA0),"+v"(pA1));CMASK(pA0,pA1,0);
;   START(pA0,pA1);
;   _Pragma("unroll") for(int r=0;r<16;++r)pA1[r]=__builtin_amdgcn_exp2f(pA1[r]);
;   WAIT_BAR(0);
;   DMA_K(3,0);DMA_V(1,KSLOT);
;   ROT();
;   kload8(kf,kp0+sl_cur);
;   WAIT_BAR(3);
;   s16x4 vlo[16],vhi[16]; u32x4 pw0,pw1,pw2,pw3;
.LBB0_367:
	v_lshlrev_b32_e32 v35, 1, v34
	v_lshlrev_b32_e32 v215, 3, v34
	v_lshlrev_b32_e32 v34, 4, v34
	v_and_b32_e32 v218, 32, v35
	v_and_b32_e32 v34, 0xc0, v34
	v_and_b32_e32 v219, 24, v215
	v_lshl_or_b32 v217, v186, 8, v34
	v_add_u32_e32 v34, 0, v218
	v_add3_u32 v224, v34, v219, v217
	v_max3_f32 v34, v0, v1, v16
	v_max3_f32 v35, v2, v3, v17
	s_and_b32 s1, s1, 0x3fffffc0
	v_max3_f32 v34, v34, v18, v19
	v_max3_f32 v35, v35, v6, v7
	s_lshl_b32 s1, s1, 2
	v_max3_f32 v34, v34, v4, v5
	v_max3_f32 v35, v35, v22, v23
	s_add_i32 s34, s1, 0
	v_max3_f32 v34, v34, v20, v21
	v_max3_f32 v35, v35, v10, v11
	s_add_i32 s34, s34, 0x12000
	v_max3_f32 v34, v34, v8, v9
	v_max3_f32 v35, v35, v26, v27
	s_waitcnt vmcnt(0) lgkmcnt(0)
	s_barrier
	s_cmp_lg_u32 0, -1
	v_max3_f32 v34, v34, v24, v25
	v_max3_f32 v35, v35, v14, v15
	s_mov_b32 s72, 1
	v_max3_f32 v34, v34, v12, v13
	v_max3_f32 v35, v35, v30, v31
	s_mov_b32 s28, 0
	v_max3_f32 v34, v34, v28, v29
	v_lshlrev_b32_e32 v225, 4, v186
	v_max_f32_e32 v34, v34, v35
	v_lshl_add_u32 v216, v213, 2, s34
	v_mov_b32_e32 v35, v34
	s_nop 1
	v_permlane32_swap_b32_e32 v34, v35
	v_max_f32_e32 v34, v34, v35
	s_nop 0
	v_sub_f32_e32 v0, v0, v34
	v_sub_f32_e32 v1, v1, v34
	v_sub_f32_e32 v16, v16, v34
	v_sub_f32_e32 v17, v17, v34
	v_sub_f32_e32 v2, v2, v34
	v_sub_f32_e32 v18, v18, v34
	s_nop 0
	v_exp_f32_e32 v80, v0
	v_exp_f32_e32 v81, v1
	v_lshl_add_u64 v[0:1], v[180:181], 0, s[88:89]
	s_mov_b32 s1, m0
	s_mov_b32 m0, s42
	s_nop 0
	global_load_lds_dwordx4 v[0:1], off
	s_mov_b32 m0, s1
	s_cselect_b32 s1, 0, 0
	s_add_i32 s0, s1, s0
	v_lshl_add_u64 v[0:1], v[32:33], 0, s[86:87]
	s_add_i32 s1, s0, 0xa000
	s_mov_b32 s19, m0
	s_mov_b32 m0, s1
	s_nop 0
	global_load_lds_dwordx4 v[0:1], off
	s_mov_b32 m0, s19
	v_lshl_add_u64 v[0:1], v[32:33], 0, s[88:89]
	s_add_i32 s0, s0, 0xc000
	s_mov_b32 s1, m0
	s_mov_b32 m0, s0
	s_nop 0
	global_load_lds_dwordx4 v[0:1], off
	s_mov_b32 m0, s1
	ds_read_b128 v[168:171], v223 offset:8192
	ds_read_b128 v[160:163], v223 offset:8704
	ds_read_b128 v[172:175], v223 offset:10240
	ds_read_b128 v[156:159], v223 offset:10752
	ds_read_b128 v[164:167], v223 offset:12288
	ds_read_b128 v[148:151], v223 offset:12800
	ds_read_b128 v[152:155], v223 offset:14336
	ds_read_b128 v[144:147], v223 offset:14848
	v_sub_f32_e32 v3, v3, v34
	v_sub_f32_e32 v19, v19, v34
	v_sub_f32_e32 v4, v4, v34
	v_sub_f32_e32 v20, v20, v34
	v_sub_f32_e32 v5, v5, v34
	v_sub_f32_e32 v21, v21, v34
	v_sub_f32_e32 v6, v6, v34
	v_sub_f32_e32 v22, v22, v34
	v_sub_f32_e32 v7, v7, v34
	v_sub_f32_e32 v23, v23, v34
	v_sub_f32_e32 v8, v8, v34
	v_sub_f32_e32 v24, v24, v34
	v_sub_f32_e32 v9, v9, v34
	v_sub_f32_e32 v25, v25, v34
	v_sub_f32_e32 v10, v10, v34
	v_sub_f32_e32 v26, v26, v34
	v_sub_f32_e32 v11, v11, v34
	v_sub_f32_e32 v27, v27, v34
	v_sub_f32_e32 v12, v12, v34
	v_sub_f32_e32 v28, v28, v34
	v_sub_f32_e32 v13, v13, v34
	v_sub_f32_e32 v29, v29, v34
	v_sub_f32_e32 v14, v14, v34
	v_sub_f32_e32 v30, v30, v34
	v_sub_f32_e32 v15, v15, v34
	v_sub_f32_e32 v31, v31, v34
	v_exp_f32_e32 v82, v2
	v_exp_f32_e32 v83, v3
	v_exp_f32_e32 v84, v4
	v_exp_f32_e32 v85, v5
	v_exp_f32_e32 v86, v6
	v_exp_f32_e32 v87, v7
	v_exp_f32_e32 v88, v8
	v_exp_f32_e32 v89, v9
	v_exp_f32_e32 v90, v10
	v_exp_f32_e32 v91, v11
	v_exp_f32_e32 v92, v12
	v_exp_f32_e32 v93, v13
	v_exp_f32_e32 v94, v14
	v_exp_f32_e32 v95, v15
	v_exp_f32_e32 v64, v16
	v_exp_f32_e32 v65, v17
	v_exp_f32_e32 v66, v18
	v_exp_f32_e32 v67, v19
	v_exp_f32_e32 v68, v20
	v_exp_f32_e32 v69, v21
	v_exp_f32_e32 v70, v22
	v_exp_f32_e32 v71, v23
	v_exp_f32_e32 v72, v24
	v_exp_f32_e32 v73, v25
	v_exp_f32_e32 v74, v26
	v_exp_f32_e32 v75, v27
	v_exp_f32_e32 v76, v28
	v_exp_f32_e32 v77, v29
	v_exp_f32_e32 v78, v30
	v_exp_f32_e32 v79, v31
	s_waitcnt vmcnt(3) lgkmcnt(0)
	s_barrier
	s_andn2_b64 vcc, exec, s[16:17]
	v_cmp_gt_u32_e64 s[0:1], 32, v212
	v_add_f32_e32 v220, v195, v34
	s_cbranch_vccnz .LBB0_383
	s_add_u32 s20, s59, s24
	s_addc_u32 s21, s60, s25
	v_mov_b32_e32 v32, v195
	v_mov_b32_e32 v33, v195
	v_mov_b32_e32 v46, v195
	v_mov_b32_e32 v47, v195
	v_lshl_add_u64 v[182:183], s[20:21], 0, v[194:195]
	s_mov_b64 s[20:21], 0xa000
	v_mov_b32_e32 v34, v195
	v_mov_b32_e32 v35, v195
	v_mov_b32_e32 v36, v195
	v_mov_b32_e32 v37, v195
	v_mov_b32_e32 v38, v195
	v_mov_b32_e32 v39, v195
	v_mov_b32_e32 v40, v195
	v_mov_b32_e32 v41, v195
	v_mov_b32_e32 v42, v195
	v_mov_b32_e32 v43, v195
	v_mov_b32_e32 v44, v195
	v_mov_b32_e32 v45, v195
	v_mov_b64_e32 v[62:63], v[46:47]
	v_mov_b64_e32 v[16:17], v[32:33]
	v_mov_b64_e32 v[0:1], v[32:33]
	v_lshl_add_u64 v[184:185], v[180:181], 0, s[20:21]
	s_mov_b32 s20, 0
	s_movk_i32 s28, 0x4000
	s_movk_i32 s29, 0x2000
	v_mov_b32_e32 v226, 0
	s_mov_b32 s19, 6
	v_mov_b64_e32 v[60:61], v[44:45]
	v_mov_b64_e32 v[58:59], v[42:43]
	v_mov_b64_e32 v[56:57], v[40:41]
	v_mov_b64_e32 v[54:55], v[38:39]
	v_mov_b64_e32 v[52:53], v[36:37]
	v_mov_b64_e32 v[50:51], v[34:35]
	v_mov_b64_e32 v[48:49], v[32:33]
	v_mov_b64_e32 v[18:19], v[34:35]
	v_mov_b64_e32 v[20:21], v[36:37]
	v_mov_b64_e32 v[22:23], v[38:39]
	v_mov_b64_e32 v[24:25], v[40:41]
	v_mov_b64_e32 v[26:27], v[42:43]
	v_mov_b64_e32 v[28:29], v[44:45]
	v_mov_b64_e32 v[30:31], v[46:47]
	v_mov_b64_e32 v[2:3], v[34:35]
	v_mov_b64_e32 v[4:5], v[36:37]
	v_mov_b64_e32 v[6:7], v[38:39]
	v_mov_b64_e32 v[8:9], v[40:41]
	v_mov_b64_e32 v[10:11], v[42:43]
	v_mov_b64_e32 v[12:13], v[44:45]
	v_mov_b64_e32 v[14:15], v[46:47]
	v_add_u32_e32 v204, 0xfffed800, v222
	v_bfe_u32 v205, v204, 4, 6
	v_lshrrev_b32_e32 v204, 12, v204
	v_cmp_lt_u32_e64 s[98:99], 5, v204
	v_addc_co_u32_e64 v204, s[98:99], 0, v204, s[98:99]
	v_mul_u32_u24_e32 v204, 0xe00, v204
	v_lshl_add_u32 v189, v205, 2, v204
	v_add_u32_e32 v189, 0x1a800, v189
	ds_write_b32 v189, v192
	ds_write_b32 v189, v193 offset:256
	ds_write_b32 v189, v194 offset:512
	ds_write_b32 v189, v195 offset:768
	ds_write_b32 v189, v196 offset:1024
	ds_write_b32 v189, v197 offset:1280
	ds_write_b32 v189, v198 offset:1536
	ds_write_b32 v189, v199 offset:1792
	ds_write_b32 v189, v200 offset:2048
	ds_write_b32 v189, v201 offset:2304
	ds_write_b32 v189, v202 offset:2560
	ds_write_b32 v189, v203 offset:2816
	ds_write_b32 v189, v206 offset:3072
	ds_write_b32 v189, v207 offset:3328
	s_waitcnt lgkmcnt(0)
	v_add_u32_e32 v204, 0xfffed800, v222
	v_lshrrev_b32_e32 v204, 12, v204
	s_nop 0
	v_readfirstlane_b32 s98, v204
	s_cmp_gt_u32 s98, 3
	s_cbranch_scc1 .Lattn_prio_skip
	s_setprio 1
